# work balancing across workgroups: each workgroup's two FoX query blocks come from two different heads (h, h^4) so per-head forget-rate cost differences even out
# baseline (speedup 1.0000x reference)
; template<int MODE,int THRL> __device__ __forceinline__ void attn_unit(int qb,const bf16*Q,const bf16*__restrict__ K,const bf16*__restrict__ V,bf16*O,const float*__restrict__ cum,const float*__restrict__ relb,const float thr,char*shm,const int wv){
;   const int tid=::mk_tid(wv); const int lane=tid&63,r32=lane&31,hi=lane>>5; const int wid=wv;
;   const int q0=qb*QB;
;   const bf16*Qw=Q+(long)(q0+wid*QBLK)*PITCH;
;   typedef __attribute__((address_space(3))) float* lds_fptr;
;   const lds_fptr kb3=(lds_fptr)(__attribute__((address_space(3))) char*)shm+LDS_KB/4;
;   if constexpr(MODE==0){ const float cref=cum[q0]; for(int i=tid;i<q0+QB;i+=NW*64)kb3[i]=(cref-cum[i])*1.4426950408889634f; }
;   int tskip=0;
;   if constexpr(MODE==0){
;     asm volatile("s_waitcnt lgkmcnt(0)\n\ts_barrier":::"memory");
;     const int ntf=(q0+QB)/KVBLK; const int c=(tid<ntf)?(kb3[64*tid+63]<=-thr?1:0):0;
;     const int cnt=__popcll(__ballot(c));
;     const __attribute__((address_space(3))) int* cw=(const __attribute__((address_space(3))) int*)((__attribute__((address_space(3))) char*)shm+LDS_CNT);
;     if(lane==0)((__attribute__((address_space(3))) int*)cw)[wid]=cnt;
;     asm volatile("s_waitcnt lgkmcnt(0)\n\ts_barrier":::"memory");
;     tskip=(cw[0]+cw[1]+cw[2]+cw[3])&~1; tskip=__builtin_amdgcn_readfirstlane(tskip);
;   }
;   else { if(tid<128){ int bk=tid; if(tid>=16){ bk=16+(int)(__logf((float)tid*(1.f/16.f))/2.0794415416798357f*16.f); bk=bk>31?31:bk; } kb3[tid]=(relb[bk*4]-relb[31*4])*1.4426950408889634f; } }
; template <int l, int SEL> __device__ __forceinline__ void layer_body(const Args& args, LAS unsigned char* ldsp, unsigned char* lds, const int G, const int bx, const int vcu, const int wv) {
;     ...
;             for (int p = vcu; p < 256; p += G) { const int vh = p >> 5, s = p & 31;
;                 const unsigned* nr = q_ctl + 16; const float qn = sqrtf(__uint_as_float(nr[2 * vh]) + __uint_as_float(nr[2 * vh + 1])), kn = sqrtf(__uint_as_float(nr[16 + 2 * vh]) + __uint_as_float(nr[16 + 2 * vh + 1]));
;                 const float thr = 2.04f * qn * kn + 40.f;
;                 for (int half = 0; half < 2; ++half) { const int qb = half ? 63 - s : s;
;                     attn_body::attn_unit<0, 8>(qb, pj + (size_t)vh * M * 64, pj + (size_t)(8 + vh) * M * 64, pj + (size_t)(16 + vh) * M * 64, (abf*)q_yatt + vh * 64, q_cum + (size_t)vh * M, nullptr, thr, (char*)lds, wv); } }
.Lprio_l0:
	s_load_dwordx2 s[10:11], s[4:5], 0xc0
	v_writelane_b32 v255, s36, 4
	s_movk_i32 s44, 0xe000
	s_mov_b32 s8, s94
	v_writelane_b32 v255, s37, 5
	s_waitcnt lgkmcnt(0)
	s_add_u32 s3, s10, 0x14500000
	s_addc_u32 s31, s11, 0
	s_lshl_b32 s4, s68, 2
	s_lshl_b32 s5, s68, 3
	s_add_i32 s15, s4, 0
	s_lshl_b32 s66, s68, 4
	s_lshl_b32 s35, s68, 5
	s_add_i32 s15, s15, 0x24800
	s_and_b32 s67, s66, 48
	s_and_b32 s75, s5, 0x1fffffe0
	s_cmp_lg_u32 0, -1
	s_cselect_b32 s4, 0, 0
	s_add_i32 s77, s74, s4
	s_lshl_b32 s4, s69, 2
	s_add_i32 s81, s77, 0x6000
	s_add_i32 s82, s4, 0
	s_lshl_b32 s4, s68, 12
	s_mov_b64 s[36:37], s[38:39]
	s_mov_b64 s[38:39], s[96:97]
	s_mov_b32 s13, 0
	s_add_i32 s83, s4, 0
	v_mov_b32_e32 v1, 0
	s_mov_b32 s84, 0xf800000
	v_mov_b32_e32 v197, 0x260
	s_movk_i32 s85, 0x1ff
	s_add_i32 s86, 0, 0x15000
	s_mov_b32 s14, 0x3fb8aa3b
	s_add_i32 s87, 0, 0x14800
	s_mov_b64 s[16:17], 0x800
	s_lshl_b32 s18, s5, 1
	s_lshl_b32 s20, s75, 1
	v_mov_b32_e32 v202, s77
	v_mov_b32_e32 v203, s81
	s_mov_b64 s[22:23], 0x2000
	v_mov_b32_e32 v204, s74
	s_mov_b64 s[24:25], 0x4000
	s_mov_b64 s[26:27], 0x6000
	s_mov_b64 s[28:29], 0xa000
	s_mov_b32 s45, -1
	s_mov_b32 s88, 0x41000000
	s_mov_b64 s[46:47], 0x1e500000
	v_mov_b32_e32 v205, 0xff800000
	s_mov_b32 s89, s76
	s_mov_b32 s32, -1
	s_branch .LBB0_365
.Lfx0_latch:
	s_xor_b32 s89, s89, 0x80
	s_mov_b32 s32, -1

; #define q_ctl ((unsigned*)(karg_ws() + WS_CTL))
; template <int l, int SEL> __device__ __forceinline__ void layer_body(const Args& args, LAS unsigned char* ldsp, unsigned char* lds, const int G, const int bx, const int vcu, const int wv) {
;     ...
;             for (int p = vcu; p < 256; p += G) { const int vh = p >> 5, s = p & 31;
;                 const unsigned* nr = q_ctl + 16; const float qn = sqrtf(__uint_as_float(nr[2 * vh]) + __uint_as_float(nr[2 * vh + 1])), kn = sqrtf(__uint_as_float(nr[16 + 2 * vh]) + __uint_as_float(nr[16 + 2 * vh + 1]));
;                 const float thr = 2.04f * qn * kn + 40.f;
;                 for (int half = 0; half < 2; ++half) { const int qb = half ? 63 - s : s;
.LBB0_365:
	s_mov_b64 s[4:5], s[0:1]
	s_load_dwordx2 s[4:5], s[4:5], 0xc0
	s_ashr_i32 s6, s89, 5
	s_lshl_b32 s40, s6, 1
	s_ashr_i32 s41, s40, 31
	s_lshl_b64 s[40:41], s[40:41], 2
	s_waitcnt lgkmcnt(0)
	s_add_u32 s4, s4, s40
	s_addc_u32 s5, s5, s41
	global_load_dwordx2 v[2:3], v1, s[4:5] offset:64
	global_load_dwordx2 v[4:5], v1, s[4:5] offset:128
	s_ashr_i32 s7, s6, 31
	s_lshl_b64 s[4:5], s[6:7], 21
	s_add_u32 s90, s3, s4
	s_addc_u32 s91, s31, s5
	s_add_u32 s92, s90, 0x1000000
	s_addc_u32 s93, s91, 0
	s_add_u32 s94, s90, 0x2000000
	s_addc_u32 s95, s91, 0
	s_lshl_b32 s4, s89, 8
	s_and_b32 s96, s4, 0x1f00
	s_lshl_b32 s40, s6, 6
	s_lshl_b64 s[48:49], s[6:7], 16
	s_ashr_i32 s41, s40, 31
	s_xor_b32 s97, s96, 0x3f00
	s_lshl_b64 s[50:51], s[40:41], 1
	s_waitcnt vmcnt(1)
	v_add_f32_e32 v0, v2, v3
	s_waitcnt vmcnt(0)
	v_add_f32_e32 v2, v4, v5
	v_mul_f32_e32 v3, 0x4f800000, v0
	v_cmp_gt_f32_e32 vcc, s84, v0
	v_mul_f32_e32 v4, 0x4f800000, v2
	v_cmp_gt_f32_e64 s[4:5], s84, v2
	v_cndmask_b32_e32 v0, v0, v3, vcc
	v_sqrt_f32_e32 v3, v0
	v_cndmask_b32_e64 v2, v2, v4, s[4:5]
	v_sqrt_f32_e32 v4, v2
	v_add_u32_e32 v5, -1, v3
	v_fma_f32 v9, -v5, v3, v0
	v_add_u32_e32 v7, -1, v4
	v_add_u32_e32 v6, 1, v3
	v_fma_f32 v11, -v7, v4, v2
	v_cmp_ge_f32_e64 s[6:7], 0, v9
	v_add_u32_e32 v8, 1, v4
	v_fma_f32 v10, -v6, v3, v0
	v_cndmask_b32_e64 v3, v3, v5, s[6:7]
	v_cmp_ge_f32_e64 s[6:7], 0, v11
	v_fma_f32 v12, -v8, v4, v2
	s_nop 0
	v_cndmask_b32_e64 v4, v4, v7, s[6:7]
	v_cmp_lt_f32_e64 s[6:7], 0, v10
	s_nop 1
	v_cndmask_b32_e64 v3, v3, v6, s[6:7]
	v_cmp_lt_f32_e64 s[6:7], 0, v12
	v_mul_f32_e32 v5, 0x37800000, v3
	v_cndmask_b32_e32 v3, v3, v5, vcc
	v_cndmask_b32_e64 v4, v4, v8, s[6:7]
	v_mul_f32_e32 v6, 0x37800000, v4
	v_cmp_class_f32_e32 vcc, v0, v197
	v_cndmask_b32_e64 v4, v4, v6, s[4:5]
	s_mov_b32 s6, s32
	s_mov_b32 s7, s32
	v_cndmask_b32_e32 v0, v3, v0, vcc
	v_cmp_class_f32_e32 vcc, v2, v197
	v_mul_f32_e32 v0, 0x40028f5c, v0
	s_nop 0
	v_cndmask_b32_e32 v2, v4, v2, vcc
	v_fmaak_f32 v206, v0, v2, 0x42200000
	s_branch .LBB0_367
; __device__ __forceinline__ int crow(int r,int hi){return (r&3)+8*(r>>2)+4*hi;}
; #define q_cum ((float*)(karg_ws() + WS_CUM))
; template<int MODE,int THRL> __device__ __forceinline__ void attn_unit(int qb,const bf16*Q,const bf16*__restrict__ K,const bf16*__restrict__ V,bf16*O,const float*__restrict__ cum,const float*__restrict__ relb,const float thr,char*shm,const int wv){
;     ...
;   {auto rr=__builtin_amdgcn_permlane32_swap(__float_as_uint(l_reg),__float_as_uint(l_reg),false,false);l_reg=__uint_as_float(rr[0])+__uint_as_float(rr[1]);}
;   if(hi==0)wsf[32+r32]=l_reg;asm volatile("s_waitcnt lgkmcnt(0)":::"memory");
;   float rli[16];
;   #pragma unroll
;   for(int r=0;r<16;++r)rli[r]=__builtin_amdgcn_rcpf(wsf[32+crow(r,hi)]);
;   bf16*Ow=O+(long)(q0+wid*QBLK)*OPITCH;
;   { bf16*stg=(bf16*)(shm+LDS_OST)+wid*2048;
;     #pragma unroll
;     for(int r=0;r<16;++r){const int orow=crow(r,hi);
;       #pragma unroll
;       for(int d0=0;d0<2;++d0)stg[orow*64+d0*32+r32]=__float2bfloat16(o[d0][r]*rli[r]);}
;     asm volatile("s_waitcnt lgkmcnt(0)":::"memory");
;     #pragma unroll
;     for(int i=0;i<4;++i){const int row=i*8+(lane>>3),ch=lane&7; const u32x4 v=*(const u32x4*)(stg+row*64+ch*8); ATTN_STORE16(Ow+(long)row*OPITCH+ch*8,v);} }
;   asm volatile("s_waitcnt lgkmcnt(0)\n\ts_barrier":::"memory");
; template <int l, int SEL> __device__ __forceinline__ void layer_body(const Args& args, LAS unsigned char* ldsp, unsigned char* lds, const int G, const int bx, const int vcu, const int wv) {
;     ...
;                 for (int half = 0; half < 2; ++half) { const int qb = half ? 63 - s : s;
;                     attn_body::attn_unit<0, 8>(qb, pj + (size_t)vh * M * 64, pj + (size_t)(8 + vh) * M * 64, pj + (size_t)(16 + vh) * M * 64, (abf*)q_yatt + vh * 64, q_cum + (size_t)vh * M, nullptr, thr, (char*)lds, wv); } }
.LBB0_366:
	s_or_b64 exec, exec, s[4:5]
	s_waitcnt lgkmcnt(0)
	ds_read_b128 v[2:5], v214 offset:49280
	ds_read_b128 v[6:9], v214 offset:49312
	v_lshlrev_b32_e32 v49, 1, v209
	v_lshlrev_b32_e32 v50, 9, v210
	v_add3_u32 v49, s83, v49, v50
	s_waitcnt lgkmcnt(1)
	v_rcp_f32_e32 v0, v2
	v_rcp_f32_e32 v10, v3
	v_rcp_f32_e32 v11, v4
	v_rcp_f32_e32 v12, v5
	v_mul_f32_e32 v32, v32, v0
	v_mul_f32_e32 v0, v16, v0
	v_cvt_pk_bf16_f32 v0, v0, s0
	s_waitcnt lgkmcnt(0)
	v_rcp_f32_e32 v13, v6
	ds_read_b128 v[2:5], v214 offset:49344
	v_rcp_f32_e32 v14, v7
	v_rcp_f32_e32 v15, v8
	v_rcp_f32_e32 v48, v9
	ds_read_b128 v[6:9], v214 offset:49376
	ds_write_b16 v49, v0 offset:51264
	v_mul_f32_e32 v0, v33, v10
	v_cvt_pk_bf16_f32 v0, v0, s0
	ds_write_b16 v49, v0 offset:51328
	v_mul_f32_e32 v0, v17, v10
	v_cvt_pk_bf16_f32 v0, v0, s0
	ds_write_b16 v49, v0 offset:51392
	v_mul_f32_e32 v0, v34, v11
	v_cvt_pk_bf16_f32 v0, v0, s0
	ds_write_b16 v49, v0 offset:51456
	v_mul_f32_e32 v0, v18, v11
	v_cvt_pk_bf16_f32 v0, v0, s0
	ds_write_b16 v49, v0 offset:51520
	v_mul_f32_e32 v0, v35, v12
	v_cvt_pk_bf16_f32 v0, v0, s0
	ds_write_b16 v49, v0 offset:51584
	v_mul_f32_e32 v0, v19, v12
	v_cvt_pk_bf16_f32 v0, v0, s0
	ds_write_b16 v49, v0 offset:51648
	v_mul_f32_e32 v0, v36, v13
	v_cvt_pk_bf16_f32 v0, v0, s0
	ds_write_b16 v49, v0 offset:52224
	v_mul_f32_e32 v0, v20, v13
	v_cvt_pk_bf16_f32 v0, v0, s0
	ds_write_b16 v49, v0 offset:52288
	v_mul_f32_e32 v0, v37, v14
	v_cvt_pk_bf16_f32 v0, v0, s0
	ds_write_b16 v49, v0 offset:52352
	v_mul_f32_e32 v0, v21, v14
	v_cvt_pk_bf16_f32 v0, v0, s0
	ds_write_b16 v49, v0 offset:52416
	v_mul_f32_e32 v0, v38, v15
	v_cvt_pk_bf16_f32 v0, v0, s0
	ds_write_b16 v49, v0 offset:52480
	v_mul_f32_e32 v0, v22, v15
	v_cvt_pk_bf16_f32 v0, v0, s0
	s_waitcnt lgkmcnt(13)
	v_rcp_f32_e32 v2, v2
	ds_write_b16 v49, v0 offset:52544
	v_mul_f32_e32 v0, v39, v48
	v_cvt_pk_bf16_f32 v0, v0, s0
	ds_write_b16 v49, v0 offset:52608
	v_mul_f32_e32 v0, v23, v48
	v_cvt_pk_bf16_f32 v0, v0, s0
	v_rcp_f32_e32 v3, v3
	ds_write_b16 v49, v0 offset:52672
	v_mul_f32_e32 v0, v40, v2
	v_cvt_pk_bf16_f32 v0, v0, s0
	ds_write_b16 v49, v0 offset:53248
	v_mul_f32_e32 v0, v24, v2
	v_cvt_pk_bf16_f32 v0, v0, s0
	v_rcp_f32_e32 v4, v4
	ds_write_b16 v49, v0 offset:53312
	v_mul_f32_e32 v0, v41, v3
	v_cvt_pk_bf16_f32 v0, v0, s0
	ds_write_b16 v49, v0 offset:53376
	v_mul_f32_e32 v0, v25, v3
	v_cvt_pk_bf16_f32 v0, v0, s0
	v_rcp_f32_e32 v5, v5
	ds_write_b16 v49, v0 offset:53440
	v_mul_f32_e32 v0, v42, v4
	v_cvt_pk_bf16_f32 v0, v0, s0
	ds_write_b16 v49, v0 offset:53504
	v_mul_f32_e32 v0, v26, v4
	v_cvt_pk_bf16_f32 v0, v0, s0
	s_waitcnt lgkmcnt(14)
	v_rcp_f32_e32 v6, v6
	ds_write_b16 v49, v0 offset:53568
	v_mul_f32_e32 v0, v43, v5
	v_cvt_pk_bf16_f32 v0, v0, s0
	ds_write_b16 v49, v0 offset:53632
	v_mul_f32_e32 v0, v27, v5
	v_cvt_pk_bf16_f32 v0, v0, s0
	v_rcp_f32_e32 v7, v7
	ds_write_b16 v49, v0 offset:53696
	v_mul_f32_e32 v0, v44, v6
	v_cvt_pk_bf16_f32 v0, v0, s0
	ds_write_b16 v49, v0 offset:54272
	v_mul_f32_e32 v0, v28, v6
	v_cvt_pk_bf16_f32 v0, v0, s0
	v_rcp_f32_e32 v8, v8
	ds_write_b16 v49, v0 offset:54336
	v_mul_f32_e32 v0, v45, v7
	v_cvt_pk_bf16_f32 v0, v0, s0
	ds_write_b16 v49, v0 offset:54400
	v_mul_f32_e32 v0, v29, v7
	v_cvt_pk_bf16_f32 v0, v0, s0
	v_rcp_f32_e32 v9, v9
	ds_write_b16 v49, v0 offset:54464
	v_mul_f32_e32 v0, v46, v8
	v_cvt_pk_bf16_f32 v0, v0, s0
	ds_write_b16 v49, v0 offset:54528
	v_mul_f32_e32 v0, v30, v8
	v_cvt_pk_bf16_f32 v0, v0, s0
	ds_write_b16 v49, v0 offset:54592
	v_mul_f32_e32 v0, v47, v9
	v_cvt_pk_bf16_f32 v0, v0, s0
	ds_write_b16 v49, v0 offset:54656
	v_mul_f32_e32 v0, v31, v9
	s_add_u32 s6, s52, s50
	v_cvt_pk_bf16_f32 v0, v0, s0
	s_addc_u32 s7, s53, s51
	s_lshl_b64 s[4:5], s[54:55], 10
	ds_write_b16 v49, v0 offset:54720
	v_lshlrev_b32_e32 v0, 1, v208
	v_cvt_pk_bf16_f32 v32, v32, s0
	s_add_u32 s4, s6, s4
	v_and_b32_e32 v0, 0x70, v0
	ds_write_b16 v49, v32 offset:51200
	s_addc_u32 s5, s7, s5
	v_lshrrev_b32_e32 v14, 3, v207
	v_add_u32_e32 v15, s83, v0
	s_waitcnt lgkmcnt(0)
	v_lshl_add_u64 v[2:3], s[4:5], 0, v[0:1]
	v_lshl_add_u32 v0, v14, 7, v15
	v_or_b32_e32 v16, 8, v14
	v_lshl_add_u64 v[10:11], v[2:3], 0, s[46:47]
	ds_read_b128 v[2:5], v0 offset:51200
	v_lshl_add_u32 v6, v16, 7, v15
	ds_read_b128 v[6:9], v6 offset:51200
	v_lshlrev_b32_e32 v0, 10, v14
	v_lshl_add_u64 v[12:13], v[10:11], 0, v[0:1]
	v_lshlrev_b32_e32 v0, 10, v16
	s_waitcnt lgkmcnt(1)
	global_store_dwordx4 v[12:13], v[2:5], off
	s_mov_b64 s[6:7], 0
	s_and_b64 vcc, exec, s[56:57]
	v_lshl_add_u64 v[2:3], v[10:11], 0, v[0:1]
	v_or_b32_e32 v0, 16, v14
	s_waitcnt lgkmcnt(0)
	global_store_dwordx4 v[2:3], v[6:9], off
	v_lshl_add_u32 v2, v0, 7, v15
	v_or_b32_e32 v14, 24, v14
	ds_read_b128 v[2:5], v2 offset:51200
	v_lshl_add_u32 v6, v14, 7, v15
	ds_read_b128 v[6:9], v6 offset:51200
	v_lshlrev_b32_e32 v0, 10, v0
	v_lshl_add_u64 v[12:13], v[10:11], 0, v[0:1]
	v_lshlrev_b32_e32 v0, 10, v14
	s_waitcnt lgkmcnt(1)
	global_store_dwordx4 v[12:13], v[2:5], off
	s_nop 1
	v_lshl_add_u64 v[2:3], v[10:11], 0, v[0:1]
	s_waitcnt lgkmcnt(0)
	global_store_dwordx4 v[2:3], v[6:9], off
	s_waitcnt lgkmcnt(0)
	s_barrier
	s_cbranch_vccnz .Lfx0_latch
	s_xor_b32 s89, s89, 0x80
	s_mov_b32 s32, 0
	s_branch .LBB0_365

; template<int MODE,int THRL> __device__ __forceinline__ void attn_unit(int qb,const bf16*Q,const bf16*__restrict__ K,const bf16*__restrict__ V,bf16*O,const float*__restrict__ cum,const float*__restrict__ relb,const float thr,char*shm,const int wv){
;   const int tid=::mk_tid(wv); const int lane=tid&63,r32=lane&31,hi=lane>>5; const int wid=wv;
;   const int q0=qb*QB;
;   const bf16*Qw=Q+(long)(q0+wid*QBLK)*PITCH;
;   typedef __attribute__((address_space(3))) float* lds_fptr;
;   const lds_fptr kb3=(lds_fptr)(__attribute__((address_space(3))) char*)shm+LDS_KB/4;
;   if constexpr(MODE==0){ const float cref=cum[q0]; for(int i=tid;i<q0+QB;i+=NW*64)kb3[i]=(cref-cum[i])*1.4426950408889634f; }
;   int tskip=0;
;   if constexpr(MODE==0){
;     asm volatile("s_waitcnt lgkmcnt(0)\n\ts_barrier":::"memory");
;     const int ntf=(q0+QB)/KVBLK; const int c=(tid<ntf)?(kb3[64*tid+63]<=-thr?1:0):0;
;     const int cnt=__popcll(__ballot(c));
;     const __attribute__((address_space(3))) int* cw=(const __attribute__((address_space(3))) int*)((__attribute__((address_space(3))) char*)shm+LDS_CNT);
;     if(lane==0)((__attribute__((address_space(3))) int*)cw)[wid]=cnt;
;     asm volatile("s_waitcnt lgkmcnt(0)\n\ts_barrier":::"memory");
;     tskip=(cw[0]+cw[1]+cw[2]+cw[3])&~1; tskip=__builtin_amdgcn_readfirstlane(tskip);
;   }
;   else { if(tid<128){ int bk=tid; if(tid>=16){ bk=16+(int)(__logf((float)tid*(1.f/16.f))/2.0794415416798357f*16.f); bk=bk>31?31:bk; } kb3[tid]=(relb[bk*4]-relb[31*4])*1.4426950408889634f; } }
; template <int l, int SEL> __device__ __forceinline__ void layer_body(const Args& args, LAS unsigned char* ldsp, unsigned char* lds, const int G, const int bx, const int vcu, const int wv) {
;     ...
;             for (int p = vcu; p < 256; p += G) { const int vh = p >> 5, s = p & 31;
;                 const unsigned* nr = q_ctl + 16; const float qn = sqrtf(__uint_as_float(nr[2 * vh]) + __uint_as_float(nr[2 * vh + 1])), kn = sqrtf(__uint_as_float(nr[16 + 2 * vh]) + __uint_as_float(nr[16 + 2 * vh + 1]));
;                 const float thr = 2.04f * qn * kn + 40.f;
;                 for (int half = 0; half < 2; ++half) { const int qb = half ? 63 - s : s;
;                     attn_body::attn_unit<0, 8>(qb, pj + (size_t)vh * M * 64, pj + (size_t)(8 + vh) * M * 64, pj + (size_t)(16 + vh) * M * 64, (abf*)q_yatt + vh * 64, q_cum + (size_t)vh * M, nullptr, thr, (char*)lds, wv); } }
.Lprio_l1:
	s_load_dwordx2 s[12:13], s[8:9], 0xc0
	s_movk_i32 s42, 0xe000
	s_mov_b32 s15, 0
	v_mov_b32_e32 v1, 0
	s_mov_b32 s80, 0xf800000
	s_waitcnt lgkmcnt(0)
	s_add_u32 s3, s12, 0x14500000
	s_addc_u32 s31, s13, 0
	s_lshl_b32 s8, s68, 2
	s_lshl_b32 s9, s68, 3
	s_lshl_b32 s35, s68, 4
	s_add_i32 s78, s8, 0
	s_add_i32 s78, s78, 0x24800
	s_and_b32 s64, s35, 48
	s_and_b32 s65, s9, 0x1fffffe0
	s_cmp_lg_u32 0, -1
	s_cselect_b32 s8, 0, 0
	s_add_i32 s66, s74, s8
	s_lshl_b32 s8, s69, 2
	s_add_i32 s67, s66, 0x6000
	s_add_i32 s17, s8, 0
	s_lshl_b32 s8, s68, 12
	s_add_i32 s79, s8, 0
	v_mov_b32_e32 v197, 0x260
	s_movk_i32 s82, 0x1ff
	s_add_i32 s83, 0, 0x15000
	s_mov_b32 s16, 0x3fb8aa3b
	s_add_i32 s84, 0, 0x14800
	s_mov_b64 s[18:19], 0x800
	s_lshl_b32 s20, s9, 1
	s_lshl_b32 s22, s65, 1
	v_mov_b32_e32 v202, s66
	v_mov_b32_e32 v203, s67
	s_mov_b64 s[24:25], 0x2000
	v_mov_b32_e32 v204, s74
	s_mov_b64 s[26:27], 0x4000
	s_mov_b64 s[28:29], 0x6000
	s_mov_b64 s[40:41], 0xa000
	s_mov_b32 s43, -1
	s_mov_b32 s85, 0x41000000
	s_mov_b64 s[44:45], 0x1e500000
	v_mov_b32_e32 v205, 0xff800000
	s_mov_b32 s86, s76
	s_mov_b32 s32, -1
	s_branch .LBB0_1405
.Lfx1_latch:
	s_xor_b32 s86, s86, 0x80
	s_mov_b32 s32, -1

; #define q_ctl ((unsigned*)(karg_ws() + WS_CTL))
; template <int l, int SEL> __device__ __forceinline__ void layer_body(const Args& args, LAS unsigned char* ldsp, unsigned char* lds, const int G, const int bx, const int vcu, const int wv) {
;     ...
;             for (int p = vcu; p < 256; p += G) { const int vh = p >> 5, s = p & 31;
;                 const unsigned* nr = q_ctl + 16; const float qn = sqrtf(__uint_as_float(nr[2 * vh]) + __uint_as_float(nr[2 * vh + 1])), kn = sqrtf(__uint_as_float(nr[16 + 2 * vh]) + __uint_as_float(nr[16 + 2 * vh + 1]));
;                 const float thr = 2.04f * qn * kn + 40.f;
;                 for (int half = 0; half < 2; ++half) { const int qb = half ? 63 - s : s;
.LBB0_1405:
	s_mov_b64 s[8:9], s[0:1]
	s_load_dwordx2 s[8:9], s[8:9], 0xc0
	s_ashr_i32 s10, s86, 5
	s_lshl_b32 s46, s10, 1
	s_ashr_i32 s47, s46, 31
	s_lshl_b64 s[46:47], s[46:47], 2
	s_waitcnt lgkmcnt(0)
	s_add_u32 s8, s8, s46
	s_addc_u32 s9, s9, s47
	global_load_dwordx2 v[2:3], v1, s[8:9] offset:64
	global_load_dwordx2 v[4:5], v1, s[8:9] offset:128
	s_ashr_i32 s11, s10, 31
	s_lshl_b64 s[8:9], s[10:11], 21
	s_add_u32 s87, s3, s8
	s_addc_u32 s88, s31, s9
	s_add_u32 s89, s87, 0x1000000
	s_addc_u32 s90, s88, 0
	s_add_u32 s91, s87, 0x2000000
	s_addc_u32 s92, s88, 0
	s_lshl_b32 s8, s86, 8
	s_and_b32 s93, s8, 0x1f00
	s_lshl_b32 s48, s10, 6
	s_lshl_b64 s[46:47], s[10:11], 16
	s_ashr_i32 s49, s48, 31
	s_xor_b32 s94, s93, 0x3f00
	s_lshl_b64 s[48:49], s[48:49], 1
	s_waitcnt vmcnt(1)
	v_add_f32_e32 v0, v2, v3
	s_waitcnt vmcnt(0)
	v_add_f32_e32 v2, v4, v5
	v_mul_f32_e32 v3, 0x4f800000, v0
	v_cmp_gt_f32_e32 vcc, s80, v0
	v_mul_f32_e32 v4, 0x4f800000, v2
	v_cmp_gt_f32_e64 s[8:9], s80, v2
	v_cndmask_b32_e32 v0, v0, v3, vcc
	v_sqrt_f32_e32 v3, v0
	v_cndmask_b32_e64 v2, v2, v4, s[8:9]
	v_sqrt_f32_e32 v4, v2
	v_add_u32_e32 v5, -1, v3
	v_fma_f32 v9, -v5, v3, v0
	v_add_u32_e32 v7, -1, v4
	v_add_u32_e32 v6, 1, v3
	v_fma_f32 v11, -v7, v4, v2
	v_cmp_ge_f32_e64 s[10:11], 0, v9
	v_add_u32_e32 v8, 1, v4
	v_fma_f32 v10, -v6, v3, v0
	v_cndmask_b32_e64 v3, v3, v5, s[10:11]
	v_cmp_ge_f32_e64 s[10:11], 0, v11
	v_fma_f32 v12, -v8, v4, v2
	s_nop 0
	v_cndmask_b32_e64 v4, v4, v7, s[10:11]
	v_cmp_lt_f32_e64 s[10:11], 0, v10
	s_nop 1
	v_cndmask_b32_e64 v3, v3, v6, s[10:11]
	v_cmp_lt_f32_e64 s[10:11], 0, v12
	v_mul_f32_e32 v5, 0x37800000, v3
	v_cndmask_b32_e32 v3, v3, v5, vcc
	v_cndmask_b32_e64 v4, v4, v8, s[10:11]
	v_mul_f32_e32 v6, 0x37800000, v4
	v_cmp_class_f32_e32 vcc, v0, v197
	v_cndmask_b32_e64 v4, v4, v6, s[8:9]
	s_mov_b32 s10, s32
	s_mov_b32 s11, s32
	v_cndmask_b32_e32 v0, v3, v0, vcc
	v_cmp_class_f32_e32 vcc, v2, v197
	v_mul_f32_e32 v0, 0x40028f5c, v0
	s_nop 0
	v_cndmask_b32_e32 v2, v4, v2, vcc
	v_fmaak_f32 v206, v0, v2, 0x42200000
	s_branch .LBB0_1407
; __device__ __forceinline__ int crow(int r,int hi){return (r&3)+8*(r>>2)+4*hi;}
; #define q_cum ((float*)(karg_ws() + WS_CUM))
; template<int MODE,int THRL> __device__ __forceinline__ void attn_unit(int qb,const bf16*Q,const bf16*__restrict__ K,const bf16*__restrict__ V,bf16*O,const float*__restrict__ cum,const float*__restrict__ relb,const float thr,char*shm,const int wv){
;     ...
;   {auto rr=__builtin_amdgcn_permlane32_swap(__float_as_uint(l_reg),__float_as_uint(l_reg),false,false);l_reg=__uint_as_float(rr[0])+__uint_as_float(rr[1]);}
;   if(hi==0)wsf[32+r32]=l_reg;asm volatile("s_waitcnt lgkmcnt(0)":::"memory");
;   float rli[16];
;   #pragma unroll
;   for(int r=0;r<16;++r)rli[r]=__builtin_amdgcn_rcpf(wsf[32+crow(r,hi)]);
;   bf16*Ow=O+(long)(q0+wid*QBLK)*OPITCH;
;   { bf16*stg=(bf16*)(shm+LDS_OST)+wid*2048;
;     #pragma unroll
;     for(int r=0;r<16;++r){const int orow=crow(r,hi);
;       #pragma unroll
;       for(int d0=0;d0<2;++d0)stg[orow*64+d0*32+r32]=__float2bfloat16(o[d0][r]*rli[r]);}
;     asm volatile("s_waitcnt lgkmcnt(0)":::"memory");
;     #pragma unroll
;     for(int i=0;i<4;++i){const int row=i*8+(lane>>3),ch=lane&7; const u32x4 v=*(const u32x4*)(stg+row*64+ch*8); ATTN_STORE16(Ow+(long)row*OPITCH+ch*8,v);} }
;   asm volatile("s_waitcnt lgkmcnt(0)\n\ts_barrier":::"memory");
; template <int l, int SEL> __device__ __forceinline__ void layer_body(const Args& args, LAS unsigned char* ldsp, unsigned char* lds, const int G, const int bx, const int vcu, const int wv) {
;     ...
;                 for (int half = 0; half < 2; ++half) { const int qb = half ? 63 - s : s;
;                     attn_body::attn_unit<0, 8>(qb, pj + (size_t)vh * M * 64, pj + (size_t)(8 + vh) * M * 64, pj + (size_t)(16 + vh) * M * 64, (abf*)q_yatt + vh * 64, q_cum + (size_t)vh * M, nullptr, thr, (char*)lds, wv); } }
.LBB0_1406:
	s_or_b64 exec, exec, s[8:9]
	s_waitcnt lgkmcnt(0)
	ds_read_b128 v[2:5], v214 offset:49280
	ds_read_b128 v[6:9], v214 offset:49312
	v_lshlrev_b32_e32 v49, 1, v209
	v_lshlrev_b32_e32 v50, 9, v210
	v_add3_u32 v49, s79, v49, v50
	s_waitcnt lgkmcnt(1)
	v_rcp_f32_e32 v0, v2
	v_rcp_f32_e32 v10, v3
	v_rcp_f32_e32 v11, v4
	v_rcp_f32_e32 v12, v5
	v_mul_f32_e32 v32, v32, v0
	v_mul_f32_e32 v0, v16, v0
	v_cvt_pk_bf16_f32 v0, v0, s0
	s_waitcnt lgkmcnt(0)
	v_rcp_f32_e32 v13, v6
	ds_read_b128 v[2:5], v214 offset:49344
	v_rcp_f32_e32 v14, v7
	v_rcp_f32_e32 v15, v8
	v_rcp_f32_e32 v48, v9
	ds_read_b128 v[6:9], v214 offset:49376
	ds_write_b16 v49, v0 offset:51264
	v_mul_f32_e32 v0, v33, v10
	v_cvt_pk_bf16_f32 v0, v0, s0
	ds_write_b16 v49, v0 offset:51328
	v_mul_f32_e32 v0, v17, v10
	v_cvt_pk_bf16_f32 v0, v0, s0
	ds_write_b16 v49, v0 offset:51392
	v_mul_f32_e32 v0, v34, v11
	v_cvt_pk_bf16_f32 v0, v0, s0
	ds_write_b16 v49, v0 offset:51456
	v_mul_f32_e32 v0, v18, v11
	v_cvt_pk_bf16_f32 v0, v0, s0
	ds_write_b16 v49, v0 offset:51520
	v_mul_f32_e32 v0, v35, v12
	v_cvt_pk_bf16_f32 v0, v0, s0
	ds_write_b16 v49, v0 offset:51584
	v_mul_f32_e32 v0, v19, v12
	v_cvt_pk_bf16_f32 v0, v0, s0
	ds_write_b16 v49, v0 offset:51648
	v_mul_f32_e32 v0, v36, v13
	v_cvt_pk_bf16_f32 v0, v0, s0
	ds_write_b16 v49, v0 offset:52224
	v_mul_f32_e32 v0, v20, v13
	v_cvt_pk_bf16_f32 v0, v0, s0
	ds_write_b16 v49, v0 offset:52288
	v_mul_f32_e32 v0, v37, v14
	v_cvt_pk_bf16_f32 v0, v0, s0
	ds_write_b16 v49, v0 offset:52352
	v_mul_f32_e32 v0, v21, v14
	v_cvt_pk_bf16_f32 v0, v0, s0
	ds_write_b16 v49, v0 offset:52416
	v_mul_f32_e32 v0, v38, v15
	v_cvt_pk_bf16_f32 v0, v0, s0
	ds_write_b16 v49, v0 offset:52480
	v_mul_f32_e32 v0, v22, v15
	v_cvt_pk_bf16_f32 v0, v0, s0
	s_waitcnt lgkmcnt(13)
	v_rcp_f32_e32 v2, v2
	ds_write_b16 v49, v0 offset:52544
	v_mul_f32_e32 v0, v39, v48
	v_cvt_pk_bf16_f32 v0, v0, s0
	ds_write_b16 v49, v0 offset:52608
	v_mul_f32_e32 v0, v23, v48
	v_cvt_pk_bf16_f32 v0, v0, s0
	v_rcp_f32_e32 v3, v3
	ds_write_b16 v49, v0 offset:52672
	v_mul_f32_e32 v0, v40, v2
	v_cvt_pk_bf16_f32 v0, v0, s0
	ds_write_b16 v49, v0 offset:53248
	v_mul_f32_e32 v0, v24, v2
	v_cvt_pk_bf16_f32 v0, v0, s0
	v_rcp_f32_e32 v4, v4
	ds_write_b16 v49, v0 offset:53312
	v_mul_f32_e32 v0, v41, v3
	v_cvt_pk_bf16_f32 v0, v0, s0
	ds_write_b16 v49, v0 offset:53376
	v_mul_f32_e32 v0, v25, v3
	v_cvt_pk_bf16_f32 v0, v0, s0
	v_rcp_f32_e32 v5, v5
	ds_write_b16 v49, v0 offset:53440
	v_mul_f32_e32 v0, v42, v4
	v_cvt_pk_bf16_f32 v0, v0, s0
	ds_write_b16 v49, v0 offset:53504
	v_mul_f32_e32 v0, v26, v4
	v_cvt_pk_bf16_f32 v0, v0, s0
	s_waitcnt lgkmcnt(14)
	v_rcp_f32_e32 v6, v6
	ds_write_b16 v49, v0 offset:53568
	v_mul_f32_e32 v0, v43, v5
	v_cvt_pk_bf16_f32 v0, v0, s0
	ds_write_b16 v49, v0 offset:53632
	v_mul_f32_e32 v0, v27, v5
	v_cvt_pk_bf16_f32 v0, v0, s0
	v_rcp_f32_e32 v7, v7
	ds_write_b16 v49, v0 offset:53696
	v_mul_f32_e32 v0, v44, v6
	v_cvt_pk_bf16_f32 v0, v0, s0
	ds_write_b16 v49, v0 offset:54272
	v_mul_f32_e32 v0, v28, v6
	v_cvt_pk_bf16_f32 v0, v0, s0
	v_rcp_f32_e32 v8, v8
	ds_write_b16 v49, v0 offset:54336
	v_mul_f32_e32 v0, v45, v7
	v_cvt_pk_bf16_f32 v0, v0, s0
	ds_write_b16 v49, v0 offset:54400
	v_mul_f32_e32 v0, v29, v7
	v_cvt_pk_bf16_f32 v0, v0, s0
	v_rcp_f32_e32 v9, v9
	ds_write_b16 v49, v0 offset:54464
	v_mul_f32_e32 v0, v46, v8
	v_cvt_pk_bf16_f32 v0, v0, s0
	ds_write_b16 v49, v0 offset:54528
	v_mul_f32_e32 v0, v30, v8
	v_cvt_pk_bf16_f32 v0, v0, s0
	ds_write_b16 v49, v0 offset:54592
	v_mul_f32_e32 v0, v47, v9
	v_cvt_pk_bf16_f32 v0, v0, s0
	ds_write_b16 v49, v0 offset:54656
	v_mul_f32_e32 v0, v31, v9
	s_add_u32 s10, s50, s48
	v_cvt_pk_bf16_f32 v0, v0, s0
	s_addc_u32 s11, s51, s49
	s_lshl_b64 s[8:9], s[52:53], 10
	ds_write_b16 v49, v0 offset:54720
	v_lshlrev_b32_e32 v0, 1, v208
	v_cvt_pk_bf16_f32 v32, v32, s0
	s_add_u32 s8, s10, s8
	v_and_b32_e32 v0, 0x70, v0
	ds_write_b16 v49, v32 offset:51200
	s_addc_u32 s9, s11, s9
	v_lshrrev_b32_e32 v14, 3, v207
	v_add_u32_e32 v15, s79, v0
	s_waitcnt lgkmcnt(0)
	v_lshl_add_u64 v[2:3], s[8:9], 0, v[0:1]
	v_lshl_add_u32 v0, v14, 7, v15
	v_or_b32_e32 v16, 8, v14
	v_lshl_add_u64 v[10:11], v[2:3], 0, s[44:45]
	ds_read_b128 v[2:5], v0 offset:51200
	v_lshl_add_u32 v6, v16, 7, v15
	ds_read_b128 v[6:9], v6 offset:51200
	v_lshlrev_b32_e32 v0, 10, v14
	v_lshl_add_u64 v[12:13], v[10:11], 0, v[0:1]
	v_lshlrev_b32_e32 v0, 10, v16
	s_waitcnt lgkmcnt(1)
	global_store_dwordx4 v[12:13], v[2:5], off
	s_mov_b64 s[10:11], 0
	s_and_b64 vcc, exec, s[54:55]
	v_lshl_add_u64 v[2:3], v[10:11], 0, v[0:1]
	v_or_b32_e32 v0, 16, v14
	s_waitcnt lgkmcnt(0)
	global_store_dwordx4 v[2:3], v[6:9], off
	v_lshl_add_u32 v2, v0, 7, v15
	v_or_b32_e32 v14, 24, v14
	ds_read_b128 v[2:5], v2 offset:51200
	v_lshl_add_u32 v6, v14, 7, v15
	ds_read_b128 v[6:9], v6 offset:51200
	v_lshlrev_b32_e32 v0, 10, v0
	v_lshl_add_u64 v[12:13], v[10:11], 0, v[0:1]
	v_lshlrev_b32_e32 v0, 10, v14
	s_waitcnt lgkmcnt(1)
	global_store_dwordx4 v[12:13], v[2:5], off
	s_nop 1
	v_lshl_add_u64 v[2:3], v[10:11], 0, v[0:1]
	s_waitcnt lgkmcnt(0)
	global_store_dwordx4 v[2:3], v[6:9], off
	s_waitcnt lgkmcnt(0)
	s_barrier
	s_cbranch_vccnz .Lfx1_latch
	s_xor_b32 s86, s86, 0x80
	s_mov_b32 s32, 0
	s_branch .LBB0_1405
